# mixer-A loop: row-sum add chain moved from the post-barrier segment head into the gaps of PV MFMAs 4..8
# speedup vs baseline: 1.0053x; 1.0028x over previous
.LBB0_488:
	s_waitcnt lgkmcnt(0)
	s_mul_i32 s0, s8, 0x9000
	v_lshlrev_b32_e32 v32, 1, v108
	v_add3_u32 v106, s0, v118, v32
	v_mov_b32_e32 v128, v33
	ds_read_b128 v[32:35], v106 offset:4608
	ds_read_b128 v[36:39], v106
	ds_read_b128 v[130:133], v106 offset:32
	ds_read_b128 v[134:137], v106 offset:4640
	s_waitcnt lgkmcnt(2)
	v_mfma_f32_32x32x16_bf16 v[48:63], v[36:39], v[64:67], 0
	v_cmp_gt_i32_e32 vcc, 0, v126
	s_and_b64 vcc, exec, vcc
	v_mfma_f32_32x32x16_bf16 v[32:47], v[32:35], v[64:67], 0
	s_waitcnt lgkmcnt(1)
	v_mfma_f32_32x32x16_bf16 v[48:63], v[130:133], v[68:71], v[48:63]
	s_waitcnt lgkmcnt(0)
	v_mfma_f32_32x32x16_bf16 v[32:47], v[134:137], v[68:71], v[32:47]
	ds_read_b128 v[130:133], v106 offset:64
	ds_read_b128 v[134:137], v106 offset:4672
	s_waitcnt lgkmcnt(1)
	v_mfma_f32_32x32x16_bf16 v[48:63], v[130:133], v[72:75], v[48:63]
	s_waitcnt lgkmcnt(0)
	v_mfma_f32_32x32x16_bf16 v[32:47], v[134:137], v[72:75], v[32:47]
	ds_read_b128 v[130:133], v106 offset:96
	ds_read_b128 v[134:137], v106 offset:4704
	s_waitcnt lgkmcnt(1)
	v_mfma_f32_32x32x16_bf16 v[48:63], v[130:133], v[76:79], v[48:63]
	s_waitcnt lgkmcnt(0)
	v_mfma_f32_32x32x16_bf16 v[32:47], v[134:137], v[76:79], v[32:47]
	ds_read2_b32 v[146:147], v127 offset0:58 offset1:59
	ds_read2_b32 v[148:149], v127 offset0:2 offset1:3
	ds_read2_b32 v[150:151], v127 offset1:1
	ds_read2_b32 v[152:153], v127 offset0:18 offset1:19
	ds_read2_b32 v[154:155], v127 offset0:16 offset1:17
	ds_read2_b32 v[156:157], v127 offset0:56 offset1:57
	ds_read2_b32 v[158:159], v127 offset0:10 offset1:11
	ds_read2_b32 v[160:161], v127 offset0:8 offset1:9
	ds_read2_b32 v[162:163], v127 offset0:50 offset1:51
	ds_read2_b32 v[164:165], v127 offset0:48 offset1:49
	ds_read2_b32 v[166:167], v127 offset0:42 offset1:43
	ds_read2_b32 v[168:169], v127 offset0:40 offset1:41
	ds_read2_b32 v[170:171], v127 offset0:34 offset1:35
	ds_read2_b32 v[172:173], v127 offset0:32 offset1:33
	ds_read2_b32 v[174:175], v127 offset0:26 offset1:27
	ds_read2_b32 v[176:177], v127 offset0:24 offset1:25
	s_waitcnt lgkmcnt(15)
	v_fmamk_f32 v107, v48, 0x3e38aa3b, v147
	v_fmamk_f32 v106, v49, 0x3e38aa3b, v146
	v_max3_f32 v129, v128, v107, v106
	s_waitcnt lgkmcnt(10)
	v_fmamk_f32 v49, v50, 0x3e38aa3b, v157
	v_fmamk_f32 v48, v51, 0x3e38aa3b, v156
	v_max3_f32 v129, v129, v49, v48
	s_waitcnt lgkmcnt(9)
	v_fmamk_f32 v134, v41, 0x3e38aa3b, v158
	s_waitcnt lgkmcnt(8)
	v_fmamk_f32 v136, v43, 0x3e38aa3b, v160
	v_fmamk_f32 v138, v45, 0x3e38aa3b, v148
	s_waitcnt lgkmcnt(7)
	v_fmamk_f32 v51, v52, 0x3e38aa3b, v163
	v_fmamk_f32 v50, v53, 0x3e38aa3b, v162
	v_max3_f32 v129, v129, v51, v50
	v_fmamk_f32 v130, v37, 0x3e38aa3b, v152
	v_fmamk_f32 v132, v39, 0x3e38aa3b, v154
	v_fmamk_f32 v140, v47, 0x3e38aa3b, v150
	s_waitcnt lgkmcnt(6)
	v_fmamk_f32 v53, v54, 0x3e38aa3b, v165
	v_fmamk_f32 v52, v55, 0x3e38aa3b, v164
	v_max3_f32 v129, v129, v53, v52
	s_waitcnt lgkmcnt(5)
	v_fmamk_f32 v55, v56, 0x3e38aa3b, v167
	v_fmamk_f32 v54, v57, 0x3e38aa3b, v166
	v_max3_f32 v129, v129, v55, v54
	s_waitcnt lgkmcnt(4)
	v_fmamk_f32 v57, v58, 0x3e38aa3b, v169
	v_fmamk_f32 v56, v59, 0x3e38aa3b, v168
	v_max3_f32 v129, v129, v57, v56
	s_waitcnt lgkmcnt(3)
	v_fmamk_f32 v59, v60, 0x3e38aa3b, v171
	v_fmamk_f32 v58, v61, 0x3e38aa3b, v170
	v_max3_f32 v129, v129, v59, v58
	s_waitcnt lgkmcnt(2)
	v_fmamk_f32 v61, v62, 0x3e38aa3b, v173
	v_fmamk_f32 v60, v63, 0x3e38aa3b, v172
	v_max3_f32 v129, v129, v61, v60
	s_waitcnt lgkmcnt(1)
	v_fmamk_f32 v63, v32, 0x3e38aa3b, v175
	v_fmamk_f32 v62, v33, 0x3e38aa3b, v174
	v_max3_f32 v129, v129, v63, v62
	s_waitcnt lgkmcnt(0)
	v_fmamk_f32 v142, v34, 0x3e38aa3b, v177
	v_fmamk_f32 v32, v35, 0x3e38aa3b, v176
	v_max3_f32 v33, v129, v142, v32
	v_fmamk_f32 v129, v36, 0x3e38aa3b, v153
	v_max3_f32 v33, v33, v129, v130
	v_fmamk_f32 v131, v38, 0x3e38aa3b, v155
	v_max3_f32 v33, v33, v131, v132
	v_fmamk_f32 v133, v40, 0x3e38aa3b, v159
	v_max3_f32 v33, v33, v133, v134
	v_fmamk_f32 v135, v42, 0x3e38aa3b, v161
	v_max3_f32 v33, v33, v135, v136
	v_fmamk_f32 v137, v44, 0x3e38aa3b, v149
	v_max3_f32 v33, v33, v137, v138
	v_fmamk_f32 v139, v46, 0x3e38aa3b, v151
	v_max3_f32 v33, v33, v139, v140
	ds_bpermute_b32 v34, v119, v33
	s_waitcnt lgkmcnt(0)
	v_max_f32_e32 v34, v34, v34
	v_max_f32_e32 v33, v33, v34
	v_sub_f32_e32 v32, v32, v33
	v_sub_f32_e32 v40, v53, v33
	v_exp_f32_e32 v53, v32
	v_sub_f32_e32 v32, v129, v33
	v_sub_f32_e32 v43, v54, v33
	v_exp_f32_e32 v54, v32
	v_sub_f32_e32 v32, v130, v33
	v_sub_f32_e32 v42, v55, v33
	v_exp_f32_e32 v55, v32
	v_sub_f32_e32 v32, v131, v33
	v_sub_f32_e32 v45, v56, v33
	v_exp_f32_e32 v56, v32
	v_sub_f32_e32 v32, v132, v33
	v_sub_f32_e32 v44, v57, v33
	v_exp_f32_e32 v57, v32
	v_sub_f32_e32 v32, v133, v33
	v_sub_f32_e32 v47, v58, v33
	v_exp_f32_e32 v58, v32
	v_sub_f32_e32 v32, v134, v33
	v_sub_f32_e32 v46, v59, v33
	v_exp_f32_e32 v59, v32
	v_sub_f32_e32 v32, v135, v33
	v_sub_f32_e32 v36, v49, v33
	v_sub_f32_e32 v49, v60, v33
	v_exp_f32_e32 v60, v32
	v_sub_f32_e32 v32, v136, v33
	v_sub_f32_e32 v37, v48, v33
	v_sub_f32_e32 v48, v61, v33
	v_exp_f32_e32 v61, v32
	v_sub_f32_e32 v32, v137, v33
	v_sub_f32_e32 v38, v51, v33
	v_sub_f32_e32 v51, v62, v33
	v_exp_f32_e32 v62, v32
	v_sub_f32_e32 v32, v138, v33
	v_sub_f32_e32 v39, v50, v33
	v_sub_f32_e32 v50, v63, v33
	v_exp_f32_e32 v63, v32
	v_sub_f32_e32 v32, v139, v33
	v_sub_f32_e32 v35, v106, v33
	v_exp_f32_e32 v106, v32
	v_sub_f32_e32 v32, v140, v33
	v_add3_u32 v140, s0, v120, v121
	v_add_u32_e32 v144, 0x3000, v140
	v_add_u32_e32 v145, 0x4000, v140
	v_sub_f32_e32 v41, v52, v33
	v_sub_f32_e32 v52, v142, v33
	ds_read2_b64 v[132:135], v144 offset0:128 offset1:130
	ds_read2_b64 v[136:139], v144 offset0:132 offset1:134
	ds_read2_b64 v[140:143], v145 offset0:160 offset1:162
	v_sub_f32_e32 v128, v128, v33
	v_sub_f32_e32 v34, v107, v33
	v_exp_f32_e32 v34, v34
	v_exp_f32_e32 v35, v35
	v_exp_f32_e32 v36, v36
	v_exp_f32_e32 v37, v37
	v_exp_f32_e32 v38, v38
	v_exp_f32_e32 v39, v39
	v_exp_f32_e32 v40, v40
	v_exp_f32_e32 v41, v41
	v_exp_f32_e32 v107, v32
	v_exp_f32_e32 v32, v128
	v_cvt_pk_bf16_f32 v128, v34, v35
	v_cvt_pk_bf16_f32 v129, v36, v37
	v_cvt_pk_bf16_f32 v130, v38, v39
	v_pk_mul_f32 v[30:31], v[30:31], v[32:33] op_sel_hi:[1,0]
	v_pk_mul_f32 v[28:29], v[28:29], v[32:33] op_sel_hi:[1,0]
	v_pk_mul_f32 v[26:27], v[26:27], v[32:33] op_sel_hi:[1,0]
	v_pk_mul_f32 v[24:25], v[24:25], v[32:33] op_sel_hi:[1,0]
	v_pk_mul_f32 v[22:23], v[22:23], v[32:33] op_sel_hi:[1,0]
	v_pk_mul_f32 v[20:21], v[20:21], v[32:33] op_sel_hi:[1,0]
	v_pk_mul_f32 v[18:19], v[18:19], v[32:33] op_sel_hi:[1,0]
	v_pk_mul_f32 v[16:17], v[16:17], v[32:33] op_sel_hi:[1,0]
	v_cvt_pk_bf16_f32 v131, v40, v41
	v_pk_mul_f32 v[14:15], v[14:15], v[32:33] op_sel_hi:[1,0]
	v_pk_mul_f32 v[12:13], v[12:13], v[32:33] op_sel_hi:[1,0]
	v_pk_mul_f32 v[10:11], v[10:11], v[32:33] op_sel_hi:[1,0]
	v_pk_mul_f32 v[8:9], v[8:9], v[32:33] op_sel_hi:[1,0]
	v_pk_mul_f32 v[6:7], v[6:7], v[32:33] op_sel_hi:[1,0]
	v_pk_mul_f32 v[4:5], v[4:5], v[32:33] op_sel_hi:[1,0]
	v_pk_mul_f32 v[2:3], v[2:3], v[32:33] op_sel_hi:[1,0]
	v_pk_mul_f32 v[0:1], v[0:1], v[32:33] op_sel_hi:[1,0]
	s_waitcnt lgkmcnt(2)
	v_mfma_f32_32x32x16_bf16 v[16:31], v[132:135], v[128:131], v[16:31]
	ds_read2_b64 v[132:135], v145 offset0:164 offset1:166
	v_exp_f32_e32 v42, v42
	v_exp_f32_e32 v43, v43
	v_exp_f32_e32 v44, v44
	v_exp_f32_e32 v45, v45
	v_exp_f32_e32 v46, v46
	v_exp_f32_e32 v47, v47
	s_waitcnt lgkmcnt(1)
	v_mfma_f32_32x32x16_bf16 v[0:15], v[140:143], v[128:131], v[0:15]
	v_exp_f32_e32 v48, v48
	v_exp_f32_e32 v49, v49
	v_cvt_pk_bf16_f32 v128, v42, v43
	v_cvt_pk_bf16_f32 v129, v44, v45
	v_cvt_pk_bf16_f32 v130, v46, v47
	v_cvt_pk_bf16_f32 v131, v48, v49
	v_exp_f32_e32 v50, v50
	v_exp_f32_e32 v51, v51
	v_mfma_f32_32x32x16_bf16 v[16:31], v[136:139], v[128:131], v[16:31]
	v_exp_f32_e32 v52, v52
	s_waitcnt lgkmcnt(0)
	v_mfma_f32_32x32x16_bf16 v[0:15], v[132:135], v[128:131], v[0:15]
	ds_read2_b64 v[132:135], v144 offset0:136 offset1:138
	ds_read2_b64 v[136:139], v145 offset0:168 offset1:170
	v_add_f32_e32 v34, 0, v34
	v_add_f32_e32 v34, v35, v34
	v_add_f32_e32 v34, v36, v34
	v_add_f32_e32 v34, v37, v34
	v_add_f32_e32 v34, v38, v34
	v_add_f32_e32 v34, v39, v34
	v_cvt_pk_bf16_f32 v128, v50, v51
	v_cvt_pk_bf16_f32 v129, v52, v53
	v_cvt_pk_bf16_f32 v130, v54, v55
	v_cvt_pk_bf16_f32 v131, v56, v57
	v_add_f32_e32 v34, v40, v34
	v_add_f32_e32 v34, v41, v34
	s_waitcnt lgkmcnt(1)
	v_mfma_f32_32x32x16_bf16 v[16:31], v[132:135], v[128:131], v[16:31]
	v_add_f32_e32 v34, v42, v34
	v_add_f32_e32 v34, v43, v34
	v_add_f32_e32 v34, v44, v34
	v_add_f32_e32 v34, v45, v34
	v_add_f32_e32 v34, v46, v34
	v_add_f32_e32 v34, v47, v34
	s_waitcnt lgkmcnt(0)
	v_mfma_f32_32x32x16_bf16 v[0:15], v[136:139], v[128:131], v[0:15]
	ds_read2_b64 v[132:135], v144 offset0:140 offset1:142
	ds_read2_b64 v[136:139], v145 offset0:172 offset1:174
	v_add_f32_e32 v34, v48, v34
	v_add_f32_e32 v34, v49, v34
	v_add_f32_e32 v34, v50, v34
	v_add_f32_e32 v34, v51, v34
	v_add_f32_e32 v34, v52, v34
	v_add_f32_e32 v34, v53, v34
	v_cvt_pk_bf16_f32 v128, v58, v59
	v_cvt_pk_bf16_f32 v129, v60, v61
	v_cvt_pk_bf16_f32 v130, v62, v63
	v_cvt_pk_bf16_f32 v131, v106, v107
	v_add_f32_e32 v34, v54, v34
	v_add_f32_e32 v34, v55, v34
	s_waitcnt lgkmcnt(1)
	v_mfma_f32_32x32x16_bf16 v[16:31], v[132:135], v[128:131], v[16:31]
	v_add_f32_e32 v34, v56, v34
	v_add_f32_e32 v34, v57, v34
	v_add_f32_e32 v34, v58, v34
	v_add_f32_e32 v34, v59, v34
	v_add_f32_e32 v34, v60, v34
	v_add_f32_e32 v34, v61, v34
	s_waitcnt lgkmcnt(0)
	v_mfma_f32_32x32x16_bf16 v[0:15], v[136:139], v[128:131], v[0:15]
	v_add_f32_e32 v34, v62, v34
	v_add_f32_e32 v34, v63, v34
	v_add_f32_e32 v34, v106, v34
	v_add_f32_e32 v34, v107, v34
	v_fmac_f32_e32 v34, v122, v32
	s_cbranch_vccnz .LBB0_492
	s_xor_b32 s8, s8, 1
	s_mul_i32 s0, s8, 0x9000
	v_add3_u32 v129, s0, v114, v115
	v_lshlrev_b32_e32 v128, 2, v113
	s_waitcnt vmcnt(0)
	ds_write_b128 v129, v[80:83]
	v_add3_u32 v129, s0, v116, v117
	ds_write_b128 v129, v[84:87]
	v_add3_u32 v128, s0, v128, v112
	s_mov_b32 s1, 0x5040100
	s_mov_b32 s0, 0x7060302
	v_perm_b32 v129, v92, v88, s1
	v_perm_b32 v130, v92, v88, s0
	v_add_u32_e32 v128, 0x3400, v128
	ds_write2_b32 v128, v129, v130 offset1:34
	v_perm_b32 v129, v93, v89, s1
	v_perm_b32 v130, v93, v89, s0
	ds_write2_b32 v128, v129, v130 offset0:68 offset1:102
	v_perm_b32 v129, v94, v90, s1
	v_perm_b32 v130, v94, v90, s0
	ds_write2_b32 v128, v129, v130 offset0:136 offset1:170
	v_subrev_co_u32_e32 v126, vcc, 1, v126
	v_perm_b32 v129, v95, v91, s1
	v_perm_b32 v130, v95, v91, s0
	s_and_b64 vcc, exec, vcc
	ds_write2_b32 v128, v129, v130 offset0:204 offset1:238
	s_cbranch_vccnz .LBB0_491
	v_add_u32_e32 v90, 1, v123
	v_mad_i64_i32 v[80:81], s[0:1], v125, s17, v[102:103]
	v_mad_i64_i32 v[84:85], s[0:1], v124, s17, v[104:105]
	v_mad_u64_u32 v[88:89], s[0:1], v123, s17, v[100:101]
	v_mad_u64_u32 v[92:93], s[0:1], v90, s17, v[100:101]
	global_load_dwordx4 v[80:83], v[80:81], off offset:512
	s_nop 0
	global_load_dwordx4 v[84:87], v[84:85], off offset:512
	s_nop 0
	global_load_dwordx4 v[88:91], v[88:89], off offset:1024
	s_nop 0
	global_load_dwordx4 v[92:95], v[92:93], off offset:1024

.LBB0_493:
	s_and_b64 vcc, exec, s[0:1]
	s_cbranch_vccnz .LBB0_711
	v_mov_b32_e32 v122, v34
	s_branch .LBB0_488
